# ctx self-attention items reassigned to the blocks with the short edge neighbourhood items (pure reassignment)
# baseline (speedup 1.0000x reference)
.LBB0_321:
	s_add_i32 s2, s2, s50
	s_add_i32 s3, s3, s50
	s_add_i32 s25, s25, s42
	s_cmpk_lg_i32 s50, 0x200
	s_cbranch_scc1 .Lnat_noremap
	s_cmpk_lt_i32 s2, 0x400
	s_cbranch_scc1 .Lnat_noremap
	s_sub_i32 s0, s2, 0x400
	s_cmpk_gt_i32 s0, 0x1ff
	s_cbranch_scc1 .Lnat_noremap
	s_bfe_u32 s1, s0, 0x30003
	s_cmp_eq_u32 s1, 0
	s_cbranch_scc1 .Lnat_ctx_ok
	s_cmp_eq_u32 s1, 7
	s_cbranch_scc0 .Lnat_ctx_skip
.Lnat_ctx_ok:
	s_lshr_b32 s3, s0, 6
	s_lshl_b32 s3, s3, 4
	s_and_b32 s0, s0, 7
	s_or_b32 s3, s3, s0
	s_lshr_b32 s1, s1, 2
	s_lshl_b32 s1, s1, 3
	s_or_b32 s3, s3, s1
	s_add_i32 s2, s3, 0x400
	s_branch .Lnat_noremap
.Lnat_ctx_skip:
	s_mov_b32 s2, 0x7fffffff
.Lnat_noremap:
	v_readlane_b32 s0, v253, 42
	s_cmp_ge_i32 s2, s0
	s_cbranch_scc1 .LBB0_450
